# attention softmax butterflies via DPP moves instead of ds_bpermute (counted waits re-derived)
# speedup vs baseline: 1.0017x; 1.0017x over previous
.LBB0_779:
	v_max3_f32 v38, v73, s37, v10
	v_max3_f32 v38, v38, v18, v14
	v_max3_f32 v38, v38, v22, v26
	v_max3_f32 v38, v38, v30, v34
	v_max3_f32 v38, v38, v69, v125
	s_nop 1
	v_mov_b32_dpp v39, v38 quad_perm:[1,0,3,2] row_mask:0xf bank_mask:0xf
	v_max3_f32 v44, v53, s37, v11
	v_max3_f32 v44, v44, v19, v15
	v_max3_f32 v44, v44, v23, v27
	v_max3_f32 v44, v44, v31, v35
	s_waitcnt lgkmcnt(0)
	v_max_f32_e32 v39, v39, v39
	v_max_f32_e32 v38, v38, v39
	s_nop 1
	v_mov_b32_dpp v39, v38 quad_perm:[2,3,0,1] row_mask:0xf bank_mask:0xf
	v_max3_f32 v44, v44, v67, v71
	s_nop 1
	v_mov_b32_dpp v45, v44 quad_perm:[1,0,3,2] row_mask:0xf bank_mask:0xf
	s_waitcnt lgkmcnt(0)
	v_max_f32_e32 v39, v39, v39
	v_max_f32_e32 v38, v38, v39
	s_nop 1
	v_mov_b32_dpp v39, v38 row_half_mirror row_mask:0xf bank_mask:0xf
	s_waitcnt lgkmcnt(0)
	v_max_f32_e32 v45, v45, v45
	v_max_f32_e32 v44, v44, v45
	s_nop 1
	v_mov_b32_dpp v45, v44 quad_perm:[2,3,0,1] row_mask:0xf bank_mask:0xf
	s_waitcnt lgkmcnt(0)
	v_max_f32_e32 v39, v39, v39
	v_max_f32_e32 v38, v38, v39
	s_nop 1
	v_mov_b32_dpp v39, v38 row_mirror row_mask:0xf bank_mask:0xf
	s_waitcnt lgkmcnt(0)
	v_max_f32_e32 v45, v45, v45
	v_max_f32_e32 v44, v44, v45
	s_nop 1
	v_mov_b32_dpp v45, v44 row_half_mirror row_mask:0xf bank_mask:0xf
	s_waitcnt vmcnt(0) lgkmcnt(0)
	v_max3_f32 v38, v38, v39, v65
	v_sub_f32_e32 v39, v73, v38
	v_sub_f32_e32 v10, v10, v38
	v_mul_f32_e32 v39, 0x3fb8aa3b, v39
	v_sub_f32_e32 v18, v18, v38
	v_mul_f32_e32 v10, 0x3fb8aa3b, v10
	v_exp_f32_e32 v39, v39
	v_sub_f32_e32 v14, v14, v38
	v_mul_f32_e32 v18, 0x3fb8aa3b, v18
	v_exp_f32_e32 v10, v10
	v_sub_f32_e32 v22, v22, v38
	v_mul_f32_e32 v14, 0x3fb8aa3b, v14
	v_exp_f32_e32 v18, v18
	v_sub_f32_e32 v26, v26, v38
	v_mul_f32_e32 v22, 0x3fb8aa3b, v22
	v_exp_f32_e32 v14, v14
	v_sub_f32_e32 v30, v30, v38
	v_mul_f32_e32 v26, 0x3fb8aa3b, v26
	v_exp_f32_e32 v22, v22
	v_add_f32_e32 v40, 0, v39
	v_sub_f32_e32 v34, v34, v38
	v_mul_f32_e32 v30, 0x3fb8aa3b, v30
	v_exp_f32_e32 v26, v26
	v_add_f32_e32 v40, v10, v40
	v_exp_f32_e32 v30, v30
	v_add_f32_e32 v40, v18, v40
	v_mul_f32_e32 v34, 0x3fb8aa3b, v34
	v_sub_f32_e32 v41, v69, v38
	v_add_f32_e32 v40, v14, v40
	v_exp_f32_e32 v34, v34
	v_mul_f32_e32 v41, 0x3fb8aa3b, v41
	v_sub_f32_e32 v42, v125, v38
	v_add_f32_e32 v40, v22, v40
	v_exp_f32_e32 v41, v41
	v_mul_f32_e32 v42, 0x3fb8aa3b, v42
	v_add_f32_e32 v40, v26, v40
	v_exp_f32_e32 v42, v42
	v_add_f32_e32 v40, v30, v40
	v_add_f32_e32 v40, v34, v40
	v_add_f32_e32 v40, v41, v40
	v_add_f32_e32 v40, v42, v40
	s_nop 1
	v_mov_b32_dpp v43, v40 quad_perm:[1,0,3,2] row_mask:0xf bank_mask:0xf
	s_waitcnt lgkmcnt(0)
	v_max_f32_e32 v45, v45, v45
	v_max_f32_e32 v44, v44, v45
	s_nop 1
	v_mov_b32_dpp v45, v44 row_mirror row_mask:0xf bank_mask:0xf
	v_sub_f32_e32 v38, v65, v38
	s_waitcnt lgkmcnt(0)
	v_add_f32_e32 v40, v40, v43
	s_nop 1
	v_mov_b32_dpp v43, v40 quad_perm:[2,3,0,1] row_mask:0xf bank_mask:0xf
	v_mul_f32_e32 v38, 0x3fb8aa3b, v38
	v_exp_f32_e32 v38, v38
	s_waitcnt lgkmcnt(0)
	v_add_f32_e32 v40, v40, v43
	s_nop 1
	v_mov_b32_dpp v43, v40 row_half_mirror row_mask:0xf bank_mask:0xf
	s_waitcnt lgkmcnt(0)
	v_add_f32_e32 v40, v40, v43
	s_nop 1
	v_mov_b32_dpp v43, v40 row_mirror row_mask:0xf bank_mask:0xf
	s_waitcnt lgkmcnt(0)
	v_add_f32_e32 v40, v40, v43
	v_max3_f32 v43, v44, v45, v65
	v_sub_f32_e32 v44, v53, v43
	v_mul_f32_e32 v44, 0x3fb8aa3b, v44
	v_sub_f32_e32 v11, v11, v43
	v_exp_f32_e32 v44, v44
	v_mul_f32_e32 v11, 0x3fb8aa3b, v11
	v_sub_f32_e32 v19, v19, v43
	v_exp_f32_e32 v11, v11
	v_mul_f32_e32 v19, 0x3fb8aa3b, v19
	v_sub_f32_e32 v15, v15, v43
	v_exp_f32_e32 v19, v19
	v_mul_f32_e32 v15, 0x3fb8aa3b, v15
	v_sub_f32_e32 v23, v23, v43
	v_exp_f32_e32 v15, v15
	v_mul_f32_e32 v23, 0x3fb8aa3b, v23
	v_sub_f32_e32 v27, v27, v43
	v_add_f32_e32 v45, 0, v44
	v_exp_f32_e32 v23, v23
	v_mul_f32_e32 v27, 0x3fb8aa3b, v27
	v_sub_f32_e32 v31, v31, v43
	v_add_f32_e32 v45, v11, v45
	v_exp_f32_e32 v27, v27
	v_mul_f32_e32 v31, 0x3fb8aa3b, v31
	v_sub_f32_e32 v35, v35, v43
	v_add_f32_e32 v45, v19, v45
	v_exp_f32_e32 v31, v31
	v_mul_f32_e32 v35, 0x3fb8aa3b, v35
	v_sub_f32_e32 v49, v67, v43
	v_add_f32_e32 v45, v15, v45
	v_exp_f32_e32 v35, v35
	v_mul_f32_e32 v49, 0x3fb8aa3b, v49
	v_sub_f32_e32 v53, v71, v43
	v_add_f32_e32 v45, v23, v45
	v_exp_f32_e32 v49, v49
	v_mul_f32_e32 v53, 0x3fb8aa3b, v53
	v_add_f32_e32 v45, v27, v45
	v_exp_f32_e32 v53, v53
	v_add_f32_e32 v45, v31, v45
	v_add_f32_e32 v45, v35, v45
	v_add_f32_e32 v45, v49, v45
	v_add_f32_e32 v45, v53, v45
	s_nop 1
	v_mov_b32_dpp v67, v45 quad_perm:[1,0,3,2] row_mask:0xf bank_mask:0xf
	v_max3_f32 v71, v50, s37, v12
	v_max3_f32 v71, v71, v20, v16
	v_max3_f32 v71, v71, v24, v28
	v_max3_f32 v71, v71, v32, v36
	v_max3_f32 v71, v71, v51, v52
	s_waitcnt lgkmcnt(0)
	v_add_f32_e32 v45, v45, v67
	s_nop 1
	v_mov_b32_dpp v73, v71 quad_perm:[1,0,3,2] row_mask:0xf bank_mask:0xf
	s_nop 1
	v_mov_b32_dpp v67, v45 quad_perm:[2,3,0,1] row_mask:0xf bank_mask:0xf
	v_sub_f32_e32 v43, v65, v43
	v_mul_f32_e32 v43, 0x3fb8aa3b, v43
	v_exp_f32_e32 v43, v43
	s_waitcnt lgkmcnt(0)
	v_max_f32_e32 v73, v73, v73
	s_waitcnt lgkmcnt(0)
	v_add_f32_e32 v45, v45, v67
	v_max_f32_e32 v71, v71, v73
	s_nop 1
	v_mov_b32_dpp v67, v45 row_half_mirror row_mask:0xf bank_mask:0xf
	s_nop 1
	v_mov_b32_dpp v73, v71 quad_perm:[2,3,0,1] row_mask:0xf bank_mask:0xf
	v_add_f32_e32 v38, v38, v40
	v_div_scale_f32 v40, s[0:1], v38, v38, 1.0
	s_waitcnt lgkmcnt(0)
	v_add_f32_e32 v45, v45, v67
	s_waitcnt lgkmcnt(0)
	v_max_f32_e32 v67, v73, v73
	v_max_f32_e32 v67, v71, v67
	s_nop 1
	v_mov_b32_dpp v71, v67 row_half_mirror row_mask:0xf bank_mask:0xf
	s_nop 1
	v_mov_b32_dpp v73, v45 row_mirror row_mask:0xf bank_mask:0xf
	v_rcp_f32_e32 v69, v40
	s_waitcnt lgkmcnt(0)
	v_max_f32_e32 v71, v71, v71
	v_max_f32_e32 v67, v67, v71
	s_nop 1
	v_mov_b32_dpp v71, v67 row_mirror row_mask:0xf bank_mask:0xf
	s_waitcnt lgkmcnt(0)
	v_add_f32_e32 v45, v45, v73
	v_add_f32_e32 v43, v43, v45
	v_fma_f32 v125, -v40, v69, 1.0
	v_fmac_f32_e32 v69, v125, v69
	s_waitcnt lgkmcnt(0)
	v_max3_f32 v45, v67, v71, v65
	v_sub_f32_e32 v50, v50, v45
	v_mul_f32_e32 v50, 0x3fb8aa3b, v50
	v_sub_f32_e32 v12, v12, v45
	v_exp_f32_e32 v50, v50
	v_mul_f32_e32 v12, 0x3fb8aa3b, v12
	v_sub_f32_e32 v20, v20, v45
	v_exp_f32_e32 v12, v12
	v_mul_f32_e32 v20, 0x3fb8aa3b, v20
	v_sub_f32_e32 v16, v16, v45
	v_exp_f32_e32 v20, v20
	v_mul_f32_e32 v16, 0x3fb8aa3b, v16
	v_sub_f32_e32 v24, v24, v45
	v_exp_f32_e32 v16, v16
	v_mul_f32_e32 v24, 0x3fb8aa3b, v24
	v_sub_f32_e32 v28, v28, v45
	v_add_f32_e32 v73, 0, v50
	v_exp_f32_e32 v24, v24
	v_mul_f32_e32 v28, 0x3fb8aa3b, v28
	v_sub_f32_e32 v32, v32, v45
	v_add_f32_e32 v73, v12, v73
	v_exp_f32_e32 v28, v28
	v_mul_f32_e32 v32, 0x3fb8aa3b, v32
	v_sub_f32_e32 v36, v36, v45
	v_add_f32_e32 v73, v20, v73
	v_exp_f32_e32 v32, v32
	v_mul_f32_e32 v36, 0x3fb8aa3b, v36
	v_sub_f32_e32 v51, v51, v45
	v_add_f32_e32 v73, v16, v73
	v_exp_f32_e32 v36, v36
	v_mul_f32_e32 v51, 0x3fb8aa3b, v51
	v_sub_f32_e32 v52, v52, v45
	v_add_f32_e32 v73, v24, v73
	v_exp_f32_e32 v51, v51
	v_mul_f32_e32 v52, 0x3fb8aa3b, v52
	v_add_f32_e32 v73, v28, v73
	v_exp_f32_e32 v52, v52
	v_div_scale_f32 v125, vcc, 1.0, v38, 1.0
	v_add_f32_e32 v73, v32, v73
	v_mul_f32_e32 v126, v125, v69
	v_add_f32_e32 v73, v36, v73
	v_fma_f32 v127, -v40, v126, v125
	v_add_f32_e32 v73, v51, v73
	v_fmac_f32_e32 v126, v127, v69
	v_div_scale_f32 v67, s[0:1], v43, v43, 1.0
	v_add_f32_e32 v73, v52, v73
	v_fma_f32 v40, -v40, v126, v125
	v_rcp_f32_e32 v71, v67
	s_nop 1
	v_mov_b32_dpp v125, v73 quad_perm:[1,0,3,2] row_mask:0xf bank_mask:0xf
	v_div_fmas_f32 v40, v40, v69, v126
	v_div_fixup_f32 v69, v40, v38, 1.0
	v_fma_f32 v38, -v67, v71, 1.0
	v_fmac_f32_e32 v71, v38, v71
	s_waitcnt lgkmcnt(0)
	v_add_f32_e32 v38, v73, v125
	s_nop 1
	v_mov_b32_dpp v40, v38 quad_perm:[2,3,0,1] row_mask:0xf bank_mask:0xf
	v_max3_f32 v127, v46, s37, v13
	v_max3_f32 v127, v127, v21, v17
	v_max3_f32 v127, v127, v25, v29
	v_max3_f32 v127, v127, v33, v37
	v_max3_f32 v127, v127, v47, v48
	s_waitcnt lgkmcnt(0)
	v_add_f32_e32 v38, v38, v40
	s_nop 1
	v_mov_b32_dpp v128, v127 quad_perm:[1,0,3,2] row_mask:0xf bank_mask:0xf
	v_div_scale_f32 v73, vcc, 1.0, v43, 1.0
	s_nop 1
	v_mov_b32_dpp v40, v38 row_half_mirror row_mask:0xf bank_mask:0xf
	v_mul_f32_e32 v125, v73, v71
	v_fma_f32 v126, -v67, v125, v73
	v_fmac_f32_e32 v125, v126, v71
	v_fma_f32 v67, -v67, v125, v73
	s_waitcnt lgkmcnt(0)
	v_max_f32_e32 v73, v128, v128
	s_waitcnt lgkmcnt(0)
	v_add_f32_e32 v38, v38, v40
	v_max_f32_e32 v73, v127, v73
	s_nop 1
	v_mov_b32_dpp v40, v38 row_mirror row_mask:0xf bank_mask:0xf
	s_nop 1
	v_mov_b32_dpp v126, v73 quad_perm:[2,3,0,1] row_mask:0xf bank_mask:0xf
	s_waitcnt lgkmcnt(0)
	v_add_f32_e32 v38, v38, v40
	v_sub_f32_e32 v40, v65, v45
	s_waitcnt lgkmcnt(0)
	v_max_f32_e32 v45, v126, v126
	v_max_f32_e32 v45, v73, v45
	v_mul_f32_e32 v40, 0x3fb8aa3b, v40
	s_nop 1
	v_mov_b32_dpp v73, v45 row_half_mirror row_mask:0xf bank_mask:0xf
	v_exp_f32_e32 v40, v40
	s_nop 0
	v_add_f32_e32 v130, v40, v38
	s_waitcnt lgkmcnt(0)
	v_max_f32_e32 v38, v73, v73
	v_max_f32_e32 v38, v45, v38
	s_nop 1
	v_mov_b32_dpp v40, v38 row_mirror row_mask:0xf bank_mask:0xf
	v_div_scale_f32 v131, s[0:1], v130, v130, 1.0
	v_rcp_f32_e32 v132, v131
	v_div_fmas_f32 v45, v67, v71, v125
	s_waitcnt lgkmcnt(0)
	v_max3_f32 v71, v38, v40, v65
	v_sub_f32_e32 v33, v33, v71
	v_div_fixup_f32 v67, v45, v43, 1.0
	v_fma_f32 v43, -v131, v132, 1.0
	v_mul_f32_e32 v33, 0x3fb8aa3b, v33
	v_fmac_f32_e32 v132, v43, v132
	v_exp_f32_e32 v43, v33
	v_sub_f32_e32 v33, v37, v71
	v_mul_f32_e32 v33, 0x3fb8aa3b, v33
	v_exp_f32_e32 v45, v33
	v_sub_f32_e32 v33, v47, v71
	v_sub_f32_e32 v38, v46, v71
	v_mul_f32_e32 v33, 0x3fb8aa3b, v33
	v_mul_f32_e32 v38, 0x3fb8aa3b, v38
	v_exp_f32_e32 v73, v33
	v_sub_f32_e32 v33, v48, v71
	v_exp_f32_e32 v38, v38
	v_mul_f32_e32 v33, 0x3fb8aa3b, v33
	v_sub_f32_e32 v13, v13, v71
	v_exp_f32_e32 v125, v33
	v_cvt_pk_bf16_f32 v33, v39, s0
	v_mul_f32_e32 v13, 0x3fb8aa3b, v13
	ds_write_b16 v121, v33
	v_cvt_pk_bf16_f32 v33, v44, s0
	v_exp_f32_e32 v13, v13
	ds_write_b16 v122, v33
	v_cvt_pk_bf16_f32 v33, v50, s0
	ds_write_b16 v122, v33 offset:336
	v_cvt_pk_bf16_f32 v33, v38, s0
	v_cvt_pk_bf16_f32 v10, v10, s0
	v_sub_f32_e32 v21, v21, v71
	ds_write_b16 v122, v33 offset:672
	ds_write_b16 v121, v10 offset:32
	v_cvt_pk_bf16_f32 v10, v11, s0
	v_mul_f32_e32 v21, 0x3fb8aa3b, v21
	ds_write_b16 v122, v10 offset:32
	v_cvt_pk_bf16_f32 v10, v12, s0
	v_exp_f32_e32 v21, v21
	ds_write_b16 v122, v10 offset:368
	v_cvt_pk_bf16_f32 v10, v13, s0
	ds_write_b16 v122, v10 offset:704
	v_cvt_pk_bf16_f32 v10, v18, s0
	v_sub_f32_e32 v17, v17, v71
	ds_write_b16 v121, v10 offset:64
	v_cvt_pk_bf16_f32 v10, v19, s0
	v_mul_f32_e32 v17, 0x3fb8aa3b, v17
	ds_write_b16 v122, v10 offset:64
	v_cvt_pk_bf16_f32 v10, v20, s0
	v_exp_f32_e32 v17, v17
	ds_write_b16 v122, v10 offset:400
	v_cvt_pk_bf16_f32 v10, v21, s0
	ds_write_b16 v122, v10 offset:736
	v_cvt_pk_bf16_f32 v10, v14, s0
	v_sub_f32_e32 v25, v25, v71
	ds_write_b16 v121, v10 offset:96
	v_cvt_pk_bf16_f32 v10, v15, s0
	v_mul_f32_e32 v25, 0x3fb8aa3b, v25
	ds_write_b16 v122, v10 offset:96
	v_cvt_pk_bf16_f32 v10, v16, s0
	v_exp_f32_e32 v25, v25
	ds_write_b16 v122, v10 offset:432
	v_cvt_pk_bf16_f32 v10, v17, s0
	ds_write_b16 v122, v10 offset:768
	v_cvt_pk_bf16_f32 v10, v22, s0
	v_sub_f32_e32 v29, v29, v71
	ds_write_b16 v121, v10 offset:128
	v_cvt_pk_bf16_f32 v10, v23, s0
	v_mul_f32_e32 v29, 0x3fb8aa3b, v29
	ds_write_b16 v122, v10 offset:128
	v_cvt_pk_bf16_f32 v10, v24, s0
	v_exp_f32_e32 v29, v29
	ds_write_b16 v122, v10 offset:464
	v_cvt_pk_bf16_f32 v10, v25, s0
	ds_write_b16 v122, v10 offset:800
	v_cvt_pk_bf16_f32 v10, v26, s0
	ds_write_b16 v121, v10 offset:160
	v_cvt_pk_bf16_f32 v10, v27, s0
	ds_write_b16 v122, v10 offset:160
	v_cvt_pk_bf16_f32 v10, v28, s0
	ds_write_b16 v122, v10 offset:496
	v_cvt_pk_bf16_f32 v10, v29, s0
	ds_write_b16 v122, v10 offset:832
	v_cvt_pk_bf16_f32 v10, v30, s0
	ds_write_b16 v121, v10 offset:192
	v_cvt_pk_bf16_f32 v10, v31, s0
	ds_write_b16 v122, v10 offset:192
	v_cvt_pk_bf16_f32 v10, v32, s0
	ds_write_b16 v122, v10 offset:528
	v_cvt_pk_bf16_f32 v10, v43, s0
	ds_write_b16 v122, v10 offset:864
	v_cvt_pk_bf16_f32 v10, v34, s0
	ds_write_b16 v121, v10 offset:224
	v_cvt_pk_bf16_f32 v10, v35, s0
	ds_write_b16 v122, v10 offset:224
	v_cvt_pk_bf16_f32 v10, v36, s0
	ds_write_b16 v122, v10 offset:560
	v_cvt_pk_bf16_f32 v10, v45, s0
	ds_write_b16 v122, v10 offset:896
	v_cvt_pk_bf16_f32 v10, v41, s0
	ds_write_b16 v121, v10 offset:256
	v_cvt_pk_bf16_f32 v10, v49, s0
	ds_write_b16 v122, v10 offset:256
	v_cvt_pk_bf16_f32 v10, v51, s0
	ds_write_b16 v122, v10 offset:592
	v_cvt_pk_bf16_f32 v10, v73, s0
	ds_write_b16 v122, v10 offset:928
	v_cvt_pk_bf16_f32 v10, v42, s0
	ds_write_b16 v121, v10 offset:288
	v_cvt_pk_bf16_f32 v10, v53, s0
	v_add_f32_e32 v40, 0, v38
	ds_write_b16 v122, v10 offset:288
	v_cvt_pk_bf16_f32 v10, v52, s0
	v_add_f32_e32 v40, v13, v40
	ds_write_b16 v122, v10 offset:624
	v_cvt_pk_bf16_f32 v10, v125, s0
	v_add_f32_e32 v40, v21, v40
	ds_write_b16 v122, v10 offset:960
	v_add_u32_e32 v10, s40, v56
	v_lshl_add_u32 v133, v10, 1, v112
	v_add_f32_e32 v14, v17, v40
	ds_read_b128 v[10:13], v133 offset:36864
	v_add_f32_e32 v22, v25, v14
	v_add_f32_e32 v34, v29, v22
	v_add_f32_e32 v42, v43, v34
	v_add_f32_e32 v50, v45, v42
	ds_read_b128 v[14:17], v123
	ds_read_b128 v[18:21], v133 offset:45312
	v_add_f32_e32 v50, v73, v50
	ds_read_b128 v[22:25], v133 offset:53760
	ds_read_b128 v[26:29], v123 offset:64
	ds_read_b128 v[30:33], v123 offset:256
	ds_read_b128 v[34:37], v133 offset:62208
	ds_read_b128 v[38:41], v133 offset:45376
	v_add_f32_e32 v73, v125, v50
	s_nop 1
	v_mov_b32_dpp v125, v73 quad_perm:[1,0,3,2] row_mask:0xf bank_mask:0xf
	s_waitcnt lgkmcnt(6)
	v_mfma_f32_16x16x32_bf16 v[10:13], v[10:13], v[14:17], 0
	ds_read_b128 v[42:45], v133 offset:36928
	ds_read_b128 v[46:49], v133 offset:45568
	ds_read_b128 v[50:53], v133 offset:62272
	v_sub_f32_e32 v71, v65, v71
	s_waitcnt lgkmcnt(8)
	v_mfma_f32_16x16x32_bf16 v[18:21], v[18:21], v[14:17], 0
	s_waitcnt lgkmcnt(3)
	v_add_f32_e32 v73, v73, v125
	s_nop 1
	v_mov_b32_dpp v125, v73 quad_perm:[2,3,0,1] row_mask:0xf bank_mask:0xf
	v_div_scale_f32 v134, vcc, 1.0, v130, 1.0
	v_mfma_f32_16x16x32_bf16 v[22:25], v[22:25], v[14:17], 0
	v_mul_f32_e32 v135, v134, v132
	s_waitcnt lgkmcnt(0)
	v_add_f32_e32 v73, v73, v125
	s_nop 1
	v_mov_b32_dpp v125, v73 row_half_mirror row_mask:0xf bank_mask:0xf
	v_mfma_f32_16x16x32_bf16 v[14:17], v[34:37], v[14:17], 0
	ds_read_b128 v[34:37], v133 offset:53824
	ds_read_b128 v[126:129], v133 offset:36992
	v_fma_f32 v136, -v131, v135, v134
	v_fmac_f32_e32 v135, v136, v132
	v_mfma_f32_16x16x32_bf16 v[10:13], v[42:45], v[26:29], v[10:13]
	s_waitcnt lgkmcnt(2)
	v_add_f32_e32 v73, v73, v125
	s_nop 1
	v_mov_b32_dpp v125, v73 row_mirror row_mask:0xf bank_mask:0xf
	v_fma_f32 v131, -v131, v135, v134
	v_mfma_f32_16x16x32_bf16 v[18:21], v[38:41], v[26:29], v[18:21]
	ds_read_b128 v[38:41], v133 offset:53888
	s_waitcnt lgkmcnt(2)
	v_mfma_f32_16x16x32_bf16 v[22:25], v[34:37], v[26:29], v[22:25]
	ds_read_b128 v[34:37], v123 offset:128
	ds_read_b128 v[42:45], v133 offset:45440
	v_mfma_f32_16x16x32_bf16 v[14:17], v[50:53], v[26:29], v[14:17]
	ds_read_b128 v[26:29], v123 offset:192
	s_waitcnt lgkmcnt(2)
	v_mfma_f32_16x16x32_bf16 v[10:13], v[126:129], v[34:37], v[10:13]
	ds_read_b128 v[50:53], v133 offset:62336
	ds_read_b128 v[126:129], v133 offset:45504
	s_waitcnt lgkmcnt(3)
	v_mfma_f32_16x16x32_bf16 v[18:21], v[42:45], v[34:37], v[18:21]
	ds_read_b128 v[42:45], v133 offset:37056
	v_mfma_f32_16x16x32_bf16 v[22:25], v[38:41], v[34:37], v[22:25]
	ds_read_b128 v[38:41], v133 offset:62400
	s_waitcnt lgkmcnt(3)
	v_mfma_f32_16x16x32_bf16 v[14:17], v[50:53], v[34:37], v[14:17]
	v_mul_f32_e32 v34, 0x3fb8aa3b, v71
	v_exp_f32_e32 v50, v34
	ds_read_b128 v[34:37], v133 offset:37120
	s_waitcnt lgkmcnt(2)
	v_mfma_f32_16x16x32_bf16 v[10:13], v[42:45], v[26:29], v[10:13]
	ds_read_b128 v[42:45], v133 offset:53952
	v_add_f32_e32 v51, v73, v125
	v_add_f32_e32 v73, v50, v51
	v_div_scale_f32 v125, s[0:1], v73, v73, 1.0
	v_mfma_f32_16x16x32_bf16 v[18:21], v[126:129], v[26:29], v[18:21]
	v_rcp_f32_e32 v126, v125
	ds_read_b128 v[50:53], v133 offset:54016
	v_div_fmas_f32 v71, v131, v132, v135
	s_waitcnt lgkmcnt(1)
	v_mfma_f32_16x16x32_bf16 v[42:45], v[42:45], v[26:29], v[22:25]
	v_div_fixup_f32 v71, v71, v130, 1.0
	s_nop 1
	v_fma_f32 v22, -v125, v126, 1.0
	v_fmac_f32_e32 v126, v22, v126
	v_mfma_f32_16x16x32_bf16 v[38:41], v[38:41], v[26:29], v[14:17]
	ds_bpermute_b32 v26, v102, v69
	ds_bpermute_b32 v27, v102, v67
	ds_bpermute_b32 v28, v102, v71
	v_div_scale_f32 v14, vcc, 1.0, v73, 1.0
	v_mul_f32_e32 v15, v14, v126
	v_mfma_f32_16x16x32_bf16 v[22:25], v[34:37], v[30:33], v[10:13]
	s_nop 2
	v_fma_f32 v10, -v125, v15, v14
	v_fmac_f32_e32 v15, v10, v126
	ds_read_b128 v[10:13], v133 offset:62464
	v_fma_f32 v14, -v125, v15, v14
	v_div_fmas_f32 v14, v14, v126, v15
	v_div_fixup_f32 v29, v14, v73, 1.0
	ds_bpermute_b32 v29, v102, v29
	v_mfma_f32_16x16x32_bf16 v[18:21], v[46:49], v[30:33], v[18:21]
	v_cmp_lt_i32_e32 vcc, 0, v103
	s_waitcnt lgkmcnt(5)
	v_mfma_f32_16x16x32_bf16 v[14:17], v[50:53], v[30:33], v[42:45]
	s_waitcnt lgkmcnt(1)
	v_mfma_f32_16x16x32_bf16 v[10:13], v[10:13], v[30:33], v[38:41]
	s_and_saveexec_b64 s[0:1], vcc
	s_cbranch_execz .LBB0_772
	v_cmp_ne_u32_e32 vcc, 1, v103
	s_and_saveexec_b64 s[22:23], vcc
	s_xor_b64 s[22:23], exec, s[22:23]
	s_cbranch_execz .LBB0_782
	s_waitcnt lgkmcnt(0)
	v_cndmask_b32_e64 v26, v29, v28, s[4:5]
